# v48 + MLA softmax row-sum accumulated in 4 independent partial sums instead of one 32-long dependent chain
# baseline (speedup 1.0000x reference)
.LBB0_520:
	v_cndmask_b32_e64 v167, v145, v167, s[4:5]
	v_mul_f32_e32 v145, 0xbdd53b94, v167
	v_fmamk_f32 v84, v84, 0x3dd53b94, v145
	v_fmamk_f32 v85, v85, 0x3dd53b94, v145
	v_fmamk_f32 v86, v86, 0x3dd53b94, v145
	v_fmamk_f32 v87, v87, 0x3dd53b94, v145
	v_fmamk_f32 v88, v88, 0x3dd53b94, v145
	v_fmamk_f32 v89, v89, 0x3dd53b94, v145
	v_fmamk_f32 v90, v90, 0x3dd53b94, v145
	v_fmamk_f32 v91, v91, 0x3dd53b94, v145
	v_fmamk_f32 v92, v92, 0x3dd53b94, v145
	v_fmamk_f32 v93, v93, 0x3dd53b94, v145
	v_fmamk_f32 v94, v94, 0x3dd53b94, v145
	v_fmamk_f32 v95, v95, 0x3dd53b94, v145
	v_fmamk_f32 v96, v96, 0x3dd53b94, v145
	v_fmamk_f32 v97, v97, 0x3dd53b94, v145
	v_fmamk_f32 v98, v98, 0x3dd53b94, v145
	v_fmamk_f32 v99, v99, 0x3dd53b94, v145
	v_fmamk_f32 v68, v68, 0x3dd53b94, v145
	v_fmamk_f32 v69, v69, 0x3dd53b94, v145
	v_fmamk_f32 v70, v70, 0x3dd53b94, v145
	v_fmamk_f32 v71, v71, 0x3dd53b94, v145
	v_fmamk_f32 v72, v72, 0x3dd53b94, v145
	v_fmamk_f32 v73, v73, 0x3dd53b94, v145
	v_fmamk_f32 v74, v74, 0x3dd53b94, v145
	v_fmamk_f32 v75, v75, 0x3dd53b94, v145
	v_fmamk_f32 v76, v76, 0x3dd53b94, v145
	v_fmamk_f32 v77, v77, 0x3dd53b94, v145
	v_fmamk_f32 v78, v78, 0x3dd53b94, v145
	v_fmamk_f32 v79, v79, 0x3dd53b94, v145
	v_fmamk_f32 v80, v80, 0x3dd53b94, v145
	v_fmamk_f32 v81, v81, 0x3dd53b94, v145
	v_fmamk_f32 v82, v82, 0x3dd53b94, v145
	v_fmac_f32_e32 v145, 0x3dd53b94, v83
	v_exp_f32_e32 v83, v84
	v_exp_f32_e32 v84, v85
	v_exp_f32_e32 v85, v86
	v_exp_f32_e32 v86, v87
	v_exp_f32_e32 v87, v88
	v_exp_f32_e32 v88, v89
	v_exp_f32_e32 v89, v90
	v_exp_f32_e32 v90, v91
	v_exp_f32_e32 v91, v92
	v_exp_f32_e32 v92, v93
	v_exp_f32_e32 v93, v94
	v_exp_f32_e32 v94, v95
	v_exp_f32_e32 v95, v96
	v_exp_f32_e32 v96, v97
	v_exp_f32_e32 v97, v98
	v_exp_f32_e32 v98, v99
	v_exp_f32_e32 v99, v68
	v_add_f32_e32 v226, v83, v84
	v_add_f32_e32 v227, v85, v86
	v_add_f32_e32 v228, v87, v88
	v_add_f32_e32 v229, v89, v90
	v_add_f32_e32 v226, v91, v226
	v_add_f32_e32 v227, v92, v227
	v_add_f32_e32 v228, v93, v228
	v_add_f32_e32 v229, v94, v229
	v_add_f32_e32 v226, v95, v226
	v_exp_f32_e32 v69, v69
	v_add_f32_e32 v227, v96, v227
	v_exp_f32_e32 v147, v70
	v_add_f32_e32 v228, v97, v228
	v_exp_f32_e32 v151, v71
	v_add_f32_e32 v229, v98, v229
	v_exp_f32_e32 v153, v72
	v_add_f32_e32 v226, v99, v226
	v_exp_f32_e32 v169, v73
	v_add_f32_e32 v227, v69, v227
	v_exp_f32_e32 v170, v74
	v_add_f32_e32 v228, v147, v228
	v_exp_f32_e32 v171, v75
	v_add_f32_e32 v229, v151, v229
	v_exp_f32_e32 v172, v76
	v_add_f32_e32 v226, v153, v226
	v_exp_f32_e32 v173, v77
	v_add_f32_e32 v227, v169, v227
	v_exp_f32_e32 v174, v78
	v_add_f32_e32 v228, v170, v228
	v_exp_f32_e32 v175, v79
	v_add_f32_e32 v229, v171, v229
	v_exp_f32_e32 v176, v80
	v_add_f32_e32 v226, v172, v226
	v_exp_f32_e32 v177, v81
	v_add_f32_e32 v227, v173, v227
	v_exp_f32_e32 v178, v82
	v_add_f32_e32 v228, v174, v228
	v_exp_f32_e32 v145, v145
	v_add_f32_e32 v229, v175, v229
	v_add_f32_e32 v226, v176, v226
	v_add_f32_e32 v227, v177, v227
	v_add_f32_e32 v228, v178, v228
	v_add_f32_e32 v229, v145, v229
	v_add_f32_e32 v226, v226, v227
	v_add_f32_e32 v228, v228, v229
	v_add_f32_e32 v68, v226, v228
	v_mov_b32_e32 v70, v68
	s_nop 1
	v_permlane32_swap_b32_e32 v68, v70
	v_add_f32_e32 v68, v68, v70
	v_fmac_f32_e32 v68, v168, v2
	v_cvt_pk_bf16_f32 v70, v83, v84
	v_cvt_pk_bf16_f32 v71, v85, v86
	v_cvt_pk_bf16_f32 v72, v87, v88
	v_cvt_pk_bf16_f32 v73, v89, v90
	v_cvt_pk_bf16_f32 v74, v91, v92
	v_cvt_pk_bf16_f32 v75, v93, v94
	v_cvt_pk_bf16_f32 v76, v95, v96
	v_cvt_pk_bf16_f32 v77, v97, v98
	v_cvt_pk_bf16_f32 v78, v99, v69
	v_cvt_pk_bf16_f32 v79, v147, v151
	v_cvt_pk_bf16_f32 v80, v153, v169
	v_cvt_pk_bf16_f32 v81, v170, v171
	v_cvt_pk_bf16_f32 v82, v172, v173
	v_cvt_pk_bf16_f32 v83, v174, v175
	v_cvt_pk_bf16_f32 v84, v176, v177
	v_cvt_pk_bf16_f32 v85, v178, v145
	v_permlane32_swap_b32_e32 v70, v72
	v_permlane32_swap_b32_e32 v71, v73
	v_permlane32_swap_b32_e32 v74, v76
	v_permlane32_swap_b32_e32 v75, v77
	v_permlane32_swap_b32_e32 v78, v80
	v_permlane32_swap_b32_e32 v79, v81
	v_permlane32_swap_b32_e32 v82, v84
	v_permlane32_swap_b32_e32 v83, v85
	ds_read_b64_tr_b16 v[86:87], v166 offset:0
	ds_read_b64_tr_b16 v[88:89], v166 offset:2048
	ds_read_b64_tr_b16 v[90:91], v166 offset:4096
	ds_read_b64_tr_b16 v[92:93], v166 offset:6144
	ds_read_b64_tr_b16 v[94:95], v166 offset:8192
	ds_read_b64_tr_b16 v[96:97], v166 offset:10240
	ds_read_b64_tr_b16 v[168:169], v166 offset:12288
	ds_read_b64_tr_b16 v[170:171], v166 offset:14336
	s_waitcnt lgkmcnt(6)
	s_nop 0
	v_mfma_f32_32x32x16_bf16 v[52:67], v[70:73], v[86:89], v[52:67]
	ds_read_b64_tr_b16 v[86:87], v166 offset:512
	ds_read_b64_tr_b16 v[88:89], v166 offset:2560
	s_waitcnt lgkmcnt(6)
	v_mfma_f32_32x32x16_bf16 v[52:67], v[74:77], v[90:93], v[52:67]
	ds_read_b64_tr_b16 v[90:91], v166 offset:4608
	ds_read_b64_tr_b16 v[92:93], v166 offset:6656
	s_waitcnt lgkmcnt(6)
	v_mfma_f32_32x32x16_bf16 v[52:67], v[78:81], v[94:97], v[52:67]
	ds_read_b64_tr_b16 v[94:95], v166 offset:8704
	ds_read_b64_tr_b16 v[96:97], v166 offset:10752
	s_waitcnt lgkmcnt(6)
	v_mfma_f32_32x32x16_bf16 v[52:67], v[82:85], v[168:171], v[52:67]
	ds_read_b64_tr_b16 v[168:169], v166 offset:12800
	ds_read_b64_tr_b16 v[170:171], v166 offset:14848
	s_waitcnt lgkmcnt(6)
	v_mfma_f32_32x32x16_bf16 v[36:51], v[70:73], v[86:89], v[36:51]
	ds_read_b64_tr_b16 v[86:87], v166 offset:1024
	ds_read_b64_tr_b16 v[88:89], v166 offset:3072
	s_waitcnt lgkmcnt(6)
	v_mfma_f32_32x32x16_bf16 v[36:51], v[74:77], v[90:93], v[36:51]
	ds_read_b64_tr_b16 v[90:91], v166 offset:5120
	ds_read_b64_tr_b16 v[92:93], v166 offset:7168
	s_waitcnt lgkmcnt(6)
	v_mfma_f32_32x32x16_bf16 v[36:51], v[78:81], v[94:97], v[36:51]
	ds_read_b64_tr_b16 v[94:95], v166 offset:9216
	ds_read_b64_tr_b16 v[96:97], v166 offset:11264
	s_waitcnt lgkmcnt(6)
	v_mfma_f32_32x32x16_bf16 v[36:51], v[82:85], v[168:171], v[36:51]
	ds_read_b64_tr_b16 v[168:169], v166 offset:13312
	ds_read_b64_tr_b16 v[170:171], v166 offset:15360
	s_waitcnt lgkmcnt(6)
	v_mfma_f32_32x32x16_bf16 v[20:35], v[70:73], v[86:89], v[20:35]
	ds_read_b64_tr_b16 v[86:87], v166 offset:1536
	ds_read_b64_tr_b16 v[88:89], v166 offset:3584
	s_waitcnt lgkmcnt(6)
	v_mfma_f32_32x32x16_bf16 v[20:35], v[74:77], v[90:93], v[20:35]
	ds_read_b64_tr_b16 v[90:91], v166 offset:5632
	ds_read_b64_tr_b16 v[92:93], v166 offset:7680
	s_waitcnt lgkmcnt(6)
	v_mfma_f32_32x32x16_bf16 v[20:35], v[78:81], v[94:97], v[20:35]
	ds_read_b64_tr_b16 v[94:95], v166 offset:9728
	ds_read_b64_tr_b16 v[96:97], v166 offset:11776
	s_waitcnt lgkmcnt(6)
	v_mfma_f32_32x32x16_bf16 v[20:35], v[82:85], v[168:171], v[20:35]
	ds_read_b64_tr_b16 v[168:169], v166 offset:13824
	ds_read_b64_tr_b16 v[170:171], v166 offset:15872
	s_waitcnt vmcnt(0) lgkmcnt(0)
	s_cmpk_eq_i32 s31, 0x48
	s_waitcnt vmcnt(0)
	s_barrier
	v_mfma_f32_32x32x16_bf16 v[4:19], v[70:73], v[86:89], v[4:19]
	v_mfma_f32_32x32x16_bf16 v[4:19], v[74:77], v[90:93], v[4:19]
	v_mfma_f32_32x32x16_bf16 v[4:19], v[78:81], v[94:97], v[4:19]
	v_mfma_f32_32x32x16_bf16 v[4:19], v[82:85], v[168:171], v[4:19]
	s_cbranch_scc0 .LBB0_512b
	s_and_saveexec_b64 s[4:5], s[0:1]
	s_cbranch_execz .LBB0_497
	ds_write_b32 v159, v68
	s_branch .LBB0_497

.LBB0_520b:
	v_cndmask_b32_e64 v167, v145, v167, s[4:5]
	v_mul_f32_e32 v145, 0xbdd53b94, v167
	v_fmamk_f32 v84, v84, 0x3dd53b94, v145
	v_fmamk_f32 v85, v85, 0x3dd53b94, v145
	v_fmamk_f32 v86, v86, 0x3dd53b94, v145
	v_fmamk_f32 v87, v87, 0x3dd53b94, v145
	v_fmamk_f32 v88, v88, 0x3dd53b94, v145
	v_fmamk_f32 v89, v89, 0x3dd53b94, v145
	v_fmamk_f32 v90, v90, 0x3dd53b94, v145
	v_fmamk_f32 v91, v91, 0x3dd53b94, v145
	v_fmamk_f32 v92, v92, 0x3dd53b94, v145
	v_fmamk_f32 v93, v93, 0x3dd53b94, v145
	v_fmamk_f32 v94, v94, 0x3dd53b94, v145
	v_fmamk_f32 v95, v95, 0x3dd53b94, v145
	v_fmamk_f32 v96, v96, 0x3dd53b94, v145
	v_fmamk_f32 v97, v97, 0x3dd53b94, v145
	v_fmamk_f32 v98, v98, 0x3dd53b94, v145
	v_fmamk_f32 v99, v99, 0x3dd53b94, v145
	v_fmamk_f32 v68, v68, 0x3dd53b94, v145
	v_fmamk_f32 v69, v69, 0x3dd53b94, v145
	v_fmamk_f32 v70, v70, 0x3dd53b94, v145
	v_fmamk_f32 v71, v71, 0x3dd53b94, v145
	v_fmamk_f32 v72, v72, 0x3dd53b94, v145
	v_fmamk_f32 v73, v73, 0x3dd53b94, v145
	v_fmamk_f32 v74, v74, 0x3dd53b94, v145
	v_fmamk_f32 v75, v75, 0x3dd53b94, v145
	v_fmamk_f32 v76, v76, 0x3dd53b94, v145
	v_fmamk_f32 v77, v77, 0x3dd53b94, v145
	v_fmamk_f32 v78, v78, 0x3dd53b94, v145
	v_fmamk_f32 v79, v79, 0x3dd53b94, v145
	v_fmamk_f32 v80, v80, 0x3dd53b94, v145
	v_fmamk_f32 v81, v81, 0x3dd53b94, v145
	v_fmamk_f32 v82, v82, 0x3dd53b94, v145
	v_fmac_f32_e32 v145, 0x3dd53b94, v83
	v_exp_f32_e32 v83, v84
	v_exp_f32_e32 v84, v85
	v_exp_f32_e32 v85, v86
	v_exp_f32_e32 v86, v87
	v_exp_f32_e32 v87, v88
	v_exp_f32_e32 v88, v89
	v_exp_f32_e32 v89, v90
	v_exp_f32_e32 v90, v91
	v_exp_f32_e32 v91, v92
	v_exp_f32_e32 v92, v93
	v_exp_f32_e32 v93, v94
	v_exp_f32_e32 v94, v95
	v_exp_f32_e32 v95, v96
	v_exp_f32_e32 v96, v97
	v_exp_f32_e32 v97, v98
	v_exp_f32_e32 v98, v99
	v_exp_f32_e32 v99, v68
	v_add_f32_e32 v226, v83, v84
	v_add_f32_e32 v227, v85, v86
	v_add_f32_e32 v228, v87, v88
	v_add_f32_e32 v229, v89, v90
	v_add_f32_e32 v226, v91, v226
	v_add_f32_e32 v227, v92, v227
	v_add_f32_e32 v228, v93, v228
	v_add_f32_e32 v229, v94, v229
	v_add_f32_e32 v226, v95, v226
	v_exp_f32_e32 v69, v69
	v_add_f32_e32 v227, v96, v227
	v_exp_f32_e32 v147, v70
	v_add_f32_e32 v228, v97, v228
	v_exp_f32_e32 v151, v71
	v_add_f32_e32 v229, v98, v229
	v_exp_f32_e32 v153, v72
	v_add_f32_e32 v226, v99, v226
	v_exp_f32_e32 v169, v73
	v_add_f32_e32 v227, v69, v227
	v_exp_f32_e32 v170, v74
	v_add_f32_e32 v228, v147, v228
	v_exp_f32_e32 v171, v75
	v_add_f32_e32 v229, v151, v229
	v_exp_f32_e32 v172, v76
	v_add_f32_e32 v226, v153, v226
	v_exp_f32_e32 v173, v77
	v_add_f32_e32 v227, v169, v227
	v_exp_f32_e32 v174, v78
	v_add_f32_e32 v228, v170, v228
	v_exp_f32_e32 v175, v79
	v_add_f32_e32 v229, v171, v229
	v_exp_f32_e32 v176, v80
	v_add_f32_e32 v226, v172, v226
	v_exp_f32_e32 v177, v81
	v_add_f32_e32 v227, v173, v227
	v_exp_f32_e32 v178, v82
	v_add_f32_e32 v228, v174, v228
	v_exp_f32_e32 v145, v145
	v_add_f32_e32 v229, v175, v229
	v_add_f32_e32 v226, v176, v226
	v_add_f32_e32 v227, v177, v227
	v_add_f32_e32 v228, v178, v228
	v_add_f32_e32 v229, v145, v229
	v_add_f32_e32 v226, v226, v227
	v_add_f32_e32 v228, v228, v229
	v_add_f32_e32 v68, v226, v228
	v_mov_b32_e32 v70, v68
	s_nop 1
	v_permlane32_swap_b32_e32 v68, v70
	v_add_f32_e32 v68, v68, v70
	v_fmac_f32_e32 v68, v168, v2
	v_cvt_pk_bf16_f32 v70, v83, v84
	v_cvt_pk_bf16_f32 v71, v85, v86
	v_cvt_pk_bf16_f32 v72, v87, v88
	v_cvt_pk_bf16_f32 v73, v89, v90
	v_cvt_pk_bf16_f32 v74, v91, v92
	v_cvt_pk_bf16_f32 v75, v93, v94
	v_cvt_pk_bf16_f32 v76, v95, v96
	v_cvt_pk_bf16_f32 v77, v97, v98
	v_cvt_pk_bf16_f32 v78, v99, v69
	v_cvt_pk_bf16_f32 v79, v147, v151
	v_cvt_pk_bf16_f32 v80, v153, v169
	v_cvt_pk_bf16_f32 v81, v170, v171
	v_cvt_pk_bf16_f32 v82, v172, v173
	v_cvt_pk_bf16_f32 v83, v174, v175
	v_cvt_pk_bf16_f32 v84, v176, v177
	v_cvt_pk_bf16_f32 v85, v178, v145
	v_permlane32_swap_b32_e32 v70, v72
	v_permlane32_swap_b32_e32 v71, v73
	v_permlane32_swap_b32_e32 v74, v76
	v_permlane32_swap_b32_e32 v75, v77
	v_permlane32_swap_b32_e32 v78, v80
	v_permlane32_swap_b32_e32 v79, v81
	v_permlane32_swap_b32_e32 v82, v84
	v_permlane32_swap_b32_e32 v83, v85
	ds_read_b64_tr_b16 v[86:87], v166 offset:16384
	ds_read_b64_tr_b16 v[88:89], v166 offset:18432
	ds_read_b64_tr_b16 v[90:91], v166 offset:20480
	ds_read_b64_tr_b16 v[92:93], v166 offset:22528
	ds_read_b64_tr_b16 v[94:95], v166 offset:24576
	ds_read_b64_tr_b16 v[96:97], v166 offset:26624
	ds_read_b64_tr_b16 v[168:169], v166 offset:28672
	ds_read_b64_tr_b16 v[170:171], v166 offset:30720
	s_waitcnt lgkmcnt(6)
	s_nop 0
	v_mfma_f32_32x32x16_bf16 v[52:67], v[70:73], v[86:89], v[52:67]
	ds_read_b64_tr_b16 v[86:87], v166 offset:16896
	ds_read_b64_tr_b16 v[88:89], v166 offset:18944
	s_waitcnt lgkmcnt(6)
	v_mfma_f32_32x32x16_bf16 v[52:67], v[74:77], v[90:93], v[52:67]
	ds_read_b64_tr_b16 v[90:91], v166 offset:20992
	ds_read_b64_tr_b16 v[92:93], v166 offset:23040
	s_waitcnt lgkmcnt(6)
	v_mfma_f32_32x32x16_bf16 v[52:67], v[78:81], v[94:97], v[52:67]
	ds_read_b64_tr_b16 v[94:95], v166 offset:25088
	ds_read_b64_tr_b16 v[96:97], v166 offset:27136
	s_waitcnt lgkmcnt(6)
	v_mfma_f32_32x32x16_bf16 v[52:67], v[82:85], v[168:171], v[52:67]
	ds_read_b64_tr_b16 v[168:169], v166 offset:29184
	ds_read_b64_tr_b16 v[170:171], v166 offset:31232
	s_waitcnt lgkmcnt(6)
	v_mfma_f32_32x32x16_bf16 v[36:51], v[70:73], v[86:89], v[36:51]
	ds_read_b64_tr_b16 v[86:87], v166 offset:17408
	ds_read_b64_tr_b16 v[88:89], v166 offset:19456
	s_waitcnt lgkmcnt(6)
	v_mfma_f32_32x32x16_bf16 v[36:51], v[74:77], v[90:93], v[36:51]
	ds_read_b64_tr_b16 v[90:91], v166 offset:21504
	ds_read_b64_tr_b16 v[92:93], v166 offset:23552
	s_waitcnt lgkmcnt(6)
	v_mfma_f32_32x32x16_bf16 v[36:51], v[78:81], v[94:97], v[36:51]
	ds_read_b64_tr_b16 v[94:95], v166 offset:25600
	ds_read_b64_tr_b16 v[96:97], v166 offset:27648
	s_waitcnt lgkmcnt(6)
	v_mfma_f32_32x32x16_bf16 v[36:51], v[82:85], v[168:171], v[36:51]
	ds_read_b64_tr_b16 v[168:169], v166 offset:29696
	ds_read_b64_tr_b16 v[170:171], v166 offset:31744
	s_waitcnt lgkmcnt(6)
	v_mfma_f32_32x32x16_bf16 v[20:35], v[70:73], v[86:89], v[20:35]
	ds_read_b64_tr_b16 v[86:87], v166 offset:17920
	ds_read_b64_tr_b16 v[88:89], v166 offset:19968
	s_waitcnt lgkmcnt(6)
	v_mfma_f32_32x32x16_bf16 v[20:35], v[74:77], v[90:93], v[20:35]
	ds_read_b64_tr_b16 v[90:91], v166 offset:22016
	ds_read_b64_tr_b16 v[92:93], v166 offset:24064
	s_waitcnt lgkmcnt(6)
	v_mfma_f32_32x32x16_bf16 v[20:35], v[78:81], v[94:97], v[20:35]
	ds_read_b64_tr_b16 v[94:95], v166 offset:26112
	ds_read_b64_tr_b16 v[96:97], v166 offset:28160
	s_waitcnt lgkmcnt(6)
	v_mfma_f32_32x32x16_bf16 v[20:35], v[82:85], v[168:171], v[20:35]
	ds_read_b64_tr_b16 v[168:169], v166 offset:30208
	ds_read_b64_tr_b16 v[170:171], v166 offset:32256
	s_waitcnt vmcnt(0) lgkmcnt(0)
	s_cmpk_eq_i32 s31, 0x48
	s_waitcnt vmcnt(0)
	s_barrier
	v_mfma_f32_32x32x16_bf16 v[4:19], v[70:73], v[86:89], v[4:19]
	v_mfma_f32_32x32x16_bf16 v[4:19], v[74:77], v[90:93], v[4:19]
	v_mfma_f32_32x32x16_bf16 v[4:19], v[78:81], v[94:97], v[4:19]
	v_mfma_f32_32x32x16_bf16 v[4:19], v[82:85], v[168:171], v[4:19]
	s_cbranch_scc0 .LBB0_512
	s_and_saveexec_b64 s[4:5], s[0:1]
	s_cbranch_execz .LBB0_497
	ds_write_b32 v159, v68
	s_branch .LBB0_497
